# heavy workgroups: the two w_out transpose items per wave interleaved (second item's 32 loads issued right after the first's, renamed registers) so their memory latencies overlap
# baseline (speedup 1.0000x reference)
; #define LAS __attribute__((address_space(3)))
; template <bool PERMUTE>
; __device__ __forceinline__ void p0_transpose_item(const float* W, int K, int N, bf16* WT, LAS float* scr, int item, int lane) {
;     const int nblk = N / 32, kb = item / nblk, nb = item % nblk, k0 = 64 * kb, n0 = 32 * nb;
;     float wv[32];
; #pragma unroll
;     for (int i = 0; i < 32; ++i) wv[i] = __builtin_nontemporal_load(W + (size_t)(k0 + 2 * i + (lane >> 5)) * N + n0 + (lane & 31));
; #pragma unroll
.LBB0_274:
	s_or_b64 exec, exec, s[0:1]
	v_and_b32_e32 v134, 31, v230
	v_lshrrev_b32_e32 v0, 5, v231
	v_lshrrev_b32_e32 v127, 3, v231
	v_lshlrev_b32_e32 v1, 3, v230
	s_barrier
	v_and_b32_e32 v130, 56, v1
	v_mov_b32_e32 v131, 0
	v_mul_u32_u24_e32 v123, 0x90, v127
	v_mul_u32_u24_e32 v125, 0x90, v134
	v_lshlrev_b32_e32 v129, 3, v0
	v_lshlrev_b32_e32 v135, 2, v0
	s_and_b32 s33, s98, 7
	s_lshr_b32 s90, s98, 3
	v_lshrrev_b32_e32 v136, 5, v231
	v_lshlrev_b32_e32 v98, 1, v130
	v_readlane_b32 s1, v253, 29
	s_lshl_b32 s0, s98, 4
	s_nop 2
	s_lshl_b32 s1, s1, 1
	s_add_i32 s0, s0, s1
	s_ashr_i32 s1, s0, 31
	s_lshr_b32 s1, s1, 27
	s_add_i32 s1, s0, s1
	s_and_b32 s2, s1, 0x7ffffe0
	s_sub_i32 s0, s0, s2
	s_lshl_b32 s1, s1, 1
	s_lshl_b32 s0, s0, 5
	s_and_b32 s2, s1, 0xffffffc0
	s_ashr_i32 s1, s0, 31
	v_readlane_b32 s12, v253, 4
	v_or_b32_e32 v2, s2, v136
	s_lshl_b64 s[4:5], s[0:1], 2
	v_readlane_b32 s26, v253, 18
	v_readlane_b32 s27, v253, 19
	s_add_u32 s4, s26, s4
	v_or_b32_e32 v8, 2, v2
	v_or_b32_e32 v10, 4, v2
	v_or_b32_e32 v12, 6, v2
	v_or_b32_e32 v14, 8, v2
	v_or_b32_e32 v16, 10, v2
	v_or_b32_e32 v18, 12, v2
	v_or_b32_e32 v20, 14, v2
	s_addc_u32 s5, s27, s5
	v_lshlrev_b32_e32 v0, 2, v134
	v_mov_b32_e32 v1, 0
	v_ashrrev_i32_e32 v3, 31, v2
	v_ashrrev_i32_e32 v9, 31, v8
	v_ashrrev_i32_e32 v11, 31, v10
	v_ashrrev_i32_e32 v13, 31, v12
	v_ashrrev_i32_e32 v15, 31, v14
	v_ashrrev_i32_e32 v17, 31, v16
	v_ashrrev_i32_e32 v19, 31, v18
	v_ashrrev_i32_e32 v21, 31, v20
	v_lshl_add_u64 v[4:5], s[4:5], 0, v[0:1]
	v_lshlrev_b64 v[6:7], 12, v[2:3]
	v_lshlrev_b64 v[8:9], 12, v[8:9]
	v_lshlrev_b64 v[10:11], 12, v[10:11]
	v_lshlrev_b64 v[12:13], 12, v[12:13]
	v_lshlrev_b64 v[14:15], 12, v[14:15]
	v_lshlrev_b64 v[16:17], 12, v[16:17]
	v_lshlrev_b64 v[18:19], 12, v[18:19]
	v_lshlrev_b64 v[20:21], 12, v[20:21]
	v_lshl_add_u64 v[6:7], v[4:5], 0, v[6:7]
	v_lshl_add_u64 v[8:9], v[4:5], 0, v[8:9]
	v_lshl_add_u64 v[10:11], v[4:5], 0, v[10:11]
	v_lshl_add_u64 v[12:13], v[4:5], 0, v[12:13]
	v_lshl_add_u64 v[14:15], v[4:5], 0, v[14:15]
	v_lshl_add_u64 v[16:17], v[4:5], 0, v[16:17]
	v_lshl_add_u64 v[18:19], v[4:5], 0, v[18:19]
	v_lshl_add_u64 v[20:21], v[4:5], 0, v[20:21]
	global_load_dword v22, v[6:7], off nt
	global_load_dword v23, v[8:9], off nt
	global_load_dword v24, v[10:11], off nt
	global_load_dword v25, v[12:13], off nt
	global_load_dword v26, v[14:15], off nt
	global_load_dword v27, v[16:17], off nt
	global_load_dword v28, v[18:19], off nt
	global_load_dword v29, v[20:21], off nt
	v_or_b32_e32 v6, 16, v2
	v_or_b32_e32 v8, 18, v2
	v_or_b32_e32 v10, 20, v2
	v_or_b32_e32 v12, 22, v2
	v_or_b32_e32 v14, 24, v2
	v_or_b32_e32 v16, 26, v2
	v_or_b32_e32 v18, 28, v2
	v_or_b32_e32 v20, 30, v2
	v_ashrrev_i32_e32 v7, 31, v6
	v_ashrrev_i32_e32 v9, 31, v8
	v_ashrrev_i32_e32 v11, 31, v10
	v_ashrrev_i32_e32 v13, 31, v12
	v_ashrrev_i32_e32 v15, 31, v14
	v_ashrrev_i32_e32 v17, 31, v16
	v_ashrrev_i32_e32 v19, 31, v18
	v_ashrrev_i32_e32 v21, 31, v20
	v_lshlrev_b64 v[6:7], 12, v[6:7]
	v_lshlrev_b64 v[8:9], 12, v[8:9]
	v_lshlrev_b64 v[10:11], 12, v[10:11]
	v_lshlrev_b64 v[12:13], 12, v[12:13]
	v_lshlrev_b64 v[14:15], 12, v[14:15]
	v_lshlrev_b64 v[16:17], 12, v[16:17]
	v_lshlrev_b64 v[18:19], 12, v[18:19]
	v_lshlrev_b64 v[20:21], 12, v[20:21]
	v_lshl_add_u64 v[6:7], v[4:5], 0, v[6:7]
	v_lshl_add_u64 v[8:9], v[4:5], 0, v[8:9]
	v_lshl_add_u64 v[10:11], v[4:5], 0, v[10:11]
	v_lshl_add_u64 v[12:13], v[4:5], 0, v[12:13]
	v_lshl_add_u64 v[14:15], v[4:5], 0, v[14:15]
	v_lshl_add_u64 v[16:17], v[4:5], 0, v[16:17]
	v_lshl_add_u64 v[18:19], v[4:5], 0, v[18:19]
	v_lshl_add_u64 v[20:21], v[4:5], 0, v[20:21]
	global_load_dword v30, v[6:7], off nt
	global_load_dword v31, v[8:9], off nt
	global_load_dword v32, v[10:11], off nt
	global_load_dword v33, v[12:13], off nt
	global_load_dword v34, v[14:15], off nt
	global_load_dword v35, v[16:17], off nt
	global_load_dword v36, v[18:19], off nt
	global_load_dword v37, v[20:21], off nt
	v_or_b32_e32 v6, 32, v2
	v_or_b32_e32 v8, 34, v2
	v_or_b32_e32 v10, 36, v2
	v_or_b32_e32 v12, 38, v2
	v_or_b32_e32 v14, 40, v2
	v_or_b32_e32 v16, 42, v2
	v_or_b32_e32 v18, 44, v2
	v_or_b32_e32 v20, 46, v2
	v_ashrrev_i32_e32 v7, 31, v6
	v_ashrrev_i32_e32 v9, 31, v8
	v_ashrrev_i32_e32 v11, 31, v10
	v_ashrrev_i32_e32 v13, 31, v12
	v_ashrrev_i32_e32 v15, 31, v14
	v_ashrrev_i32_e32 v17, 31, v16
	v_ashrrev_i32_e32 v19, 31, v18
	v_ashrrev_i32_e32 v21, 31, v20
	v_lshlrev_b64 v[6:7], 12, v[6:7]
	v_lshlrev_b64 v[8:9], 12, v[8:9]
	v_lshlrev_b64 v[10:11], 12, v[10:11]
	v_lshlrev_b64 v[12:13], 12, v[12:13]
	v_lshlrev_b64 v[14:15], 12, v[14:15]
	v_lshlrev_b64 v[16:17], 12, v[16:17]
	v_lshlrev_b64 v[18:19], 12, v[18:19]
	v_lshlrev_b64 v[20:21], 12, v[20:21]
	v_lshl_add_u64 v[6:7], v[4:5], 0, v[6:7]
	v_lshl_add_u64 v[8:9], v[4:5], 0, v[8:9]
	v_lshl_add_u64 v[10:11], v[4:5], 0, v[10:11]
	v_lshl_add_u64 v[12:13], v[4:5], 0, v[12:13]
	v_lshl_add_u64 v[14:15], v[4:5], 0, v[14:15]
	v_lshl_add_u64 v[16:17], v[4:5], 0, v[16:17]
	v_lshl_add_u64 v[18:19], v[4:5], 0, v[18:19]
	v_lshl_add_u64 v[20:21], v[4:5], 0, v[20:21]
	global_load_dword v38, v[6:7], off nt
	global_load_dword v39, v[8:9], off nt
	global_load_dword v40, v[10:11], off nt
	global_load_dword v41, v[12:13], off nt
	global_load_dword v42, v[14:15], off nt
	global_load_dword v43, v[16:17], off nt
	global_load_dword v44, v[18:19], off nt
	s_nop 0
	global_load_dword v20, v[20:21], off nt
	v_or_b32_e32 v6, 48, v2
	v_or_b32_e32 v8, 50, v2
	v_or_b32_e32 v10, 52, v2
	v_or_b32_e32 v12, 54, v2
	v_or_b32_e32 v14, 56, v2
	v_or_b32_e32 v16, 58, v2
	v_or_b32_e32 v18, 60, v2
	v_or_b32_e32 v2, 62, v2
	v_ashrrev_i32_e32 v7, 31, v6
	v_ashrrev_i32_e32 v9, 31, v8
; #define LAS __attribute__((address_space(3)))
; template <bool PERMUTE>
; __device__ __forceinline__ void p0_transpose_item(const float* W, int K, int N, bf16* WT, LAS float* scr, int item, int lane) {
;     const int nblk = N / 32, kb = item / nblk, nb = item % nblk, k0 = 64 * kb, n0 = 32 * nb;
;     float wv[32];
; #pragma unroll
;     for (int i = 0; i < 32; ++i) wv[i] = __builtin_nontemporal_load(W + (size_t)(k0 + 2 * i + (lane >> 5)) * N + n0 + (lane & 31));
; #pragma unroll
	v_ashrrev_i32_e32 v11, 31, v10
	v_ashrrev_i32_e32 v3, 31, v2
	v_lshlrev_b64 v[6:7], 12, v[6:7]
	v_lshlrev_b64 v[8:9], 12, v[8:9]
	v_lshlrev_b64 v[10:11], 12, v[10:11]
	v_ashrrev_i32_e32 v13, 31, v12
	v_ashrrev_i32_e32 v15, 31, v14
	v_ashrrev_i32_e32 v17, 31, v16
	v_ashrrev_i32_e32 v19, 31, v18
	v_lshlrev_b64 v[2:3], 12, v[2:3]
	v_lshl_add_u64 v[6:7], v[4:5], 0, v[6:7]
	v_lshl_add_u64 v[8:9], v[4:5], 0, v[8:9]
	v_lshl_add_u64 v[10:11], v[4:5], 0, v[10:11]
	v_lshlrev_b64 v[12:13], 12, v[12:13]
	v_lshlrev_b64 v[14:15], 12, v[14:15]
	v_lshlrev_b64 v[16:17], 12, v[16:17]
	v_lshlrev_b64 v[18:19], 12, v[18:19]
	v_lshl_add_u64 v[2:3], v[4:5], 0, v[2:3]
	v_lshl_add_u64 v[12:13], v[4:5], 0, v[12:13]
	v_lshl_add_u64 v[14:15], v[4:5], 0, v[14:15]
	v_lshl_add_u64 v[16:17], v[4:5], 0, v[16:17]
	v_lshl_add_u64 v[18:19], v[4:5], 0, v[18:19]
	global_load_dword v4, v[6:7], off nt
	global_load_dword v5, v[8:9], off nt
	s_nop 0
	global_load_dword v6, v[10:11], off nt
	global_load_dword v7, v[12:13], off nt
	global_load_dword v8, v[14:15], off nt
	global_load_dword v9, v[16:17], off nt
	s_nop 0
	global_load_dword v10, v[18:19], off nt
	s_nop 0
	global_load_dword v2, v[2:3], off nt
	v_readlane_b32 s11, v253, 29
	s_lshl_b32 s10, s98, 4
	s_nop 2
	s_lshl_b32 s11, s11, 1
	s_add_i32 s10, s10, s11
	s_add_i32 s10, s10, 1
	s_ashr_i32 s11, s10, 31
	s_lshr_b32 s11, s11, 27
	s_add_i32 s11, s10, s11
	s_and_b32 s6, s11, 0x7ffffe0
	s_sub_i32 s10, s10, s6
	s_lshl_b32 s11, s11, 1
	s_lshl_b32 s10, s10, 5
	s_and_b32 s6, s11, 0xffffffc0
	s_ashr_i32 s11, s10, 31
	v_readlane_b32 s12, v253, 4
	v_or_b32_e32 v174, s6, v136
	s_lshl_b64 vcc, s[10:11], 2
	v_readlane_b32 s26, v253, 18
	v_readlane_b32 s27, v253, 19
	s_add_u32 vcc_lo, s26, vcc_lo
	v_or_b32_e32 v180, 2, v174
	v_or_b32_e32 v182, 4, v174
	v_or_b32_e32 v184, 6, v174
	v_or_b32_e32 v186, 8, v174
	v_or_b32_e32 v188, 10, v174
	v_or_b32_e32 v190, 12, v174
	v_or_b32_e32 v192, 14, v174
	s_addc_u32 vcc_hi, s27, vcc_hi
	v_lshlrev_b32_e32 v172, 2, v134
	v_mov_b32_e32 v173, 0
	v_ashrrev_i32_e32 v175, 31, v174
	v_ashrrev_i32_e32 v181, 31, v180
	v_ashrrev_i32_e32 v183, 31, v182
	v_ashrrev_i32_e32 v185, 31, v184
	v_ashrrev_i32_e32 v187, 31, v186
	v_ashrrev_i32_e32 v189, 31, v188
	v_ashrrev_i32_e32 v191, 31, v190
	v_ashrrev_i32_e32 v193, 31, v192
	v_lshl_add_u64 v[176:177], vcc, 0, v[172:173]
	v_lshlrev_b64 v[178:179], 12, v[174:175]
	v_lshlrev_b64 v[180:181], 12, v[180:181]
	v_lshlrev_b64 v[182:183], 12, v[182:183]
	v_lshlrev_b64 v[184:185], 12, v[184:185]
	v_lshlrev_b64 v[186:187], 12, v[186:187]
	v_lshlrev_b64 v[188:189], 12, v[188:189]
	v_lshlrev_b64 v[190:191], 12, v[190:191]
	v_lshlrev_b64 v[192:193], 12, v[192:193]
	v_lshl_add_u64 v[178:179], v[176:177], 0, v[178:179]
	v_lshl_add_u64 v[180:181], v[176:177], 0, v[180:181]
	v_lshl_add_u64 v[182:183], v[176:177], 0, v[182:183]
	v_lshl_add_u64 v[184:185], v[176:177], 0, v[184:185]
	v_lshl_add_u64 v[186:187], v[176:177], 0, v[186:187]
	v_lshl_add_u64 v[188:189], v[176:177], 0, v[188:189]
	v_lshl_add_u64 v[190:191], v[176:177], 0, v[190:191]
	v_lshl_add_u64 v[192:193], v[176:177], 0, v[192:193]
	global_load_dword v194, v[178:179], off nt
	global_load_dword v195, v[180:181], off nt
	global_load_dword v196, v[182:183], off nt
	global_load_dword v197, v[184:185], off nt
	global_load_dword v198, v[186:187], off nt
	global_load_dword v199, v[188:189], off nt
	global_load_dword v200, v[190:191], off nt
	global_load_dword v201, v[192:193], off nt
	v_or_b32_e32 v178, 16, v174
	v_or_b32_e32 v180, 18, v174
	v_or_b32_e32 v182, 20, v174
	v_or_b32_e32 v184, 22, v174
	v_or_b32_e32 v186, 24, v174
	v_or_b32_e32 v188, 26, v174
	v_or_b32_e32 v190, 28, v174
	v_or_b32_e32 v192, 30, v174
	v_ashrrev_i32_e32 v179, 31, v178
	v_ashrrev_i32_e32 v181, 31, v180
	v_ashrrev_i32_e32 v183, 31, v182
	v_ashrrev_i32_e32 v185, 31, v184
	v_ashrrev_i32_e32 v187, 31, v186
	v_ashrrev_i32_e32 v189, 31, v188
	v_ashrrev_i32_e32 v191, 31, v190
	v_ashrrev_i32_e32 v193, 31, v192
	v_lshlrev_b64 v[178:179], 12, v[178:179]
	v_lshlrev_b64 v[180:181], 12, v[180:181]
	v_lshlrev_b64 v[182:183], 12, v[182:183]
	v_lshlrev_b64 v[184:185], 12, v[184:185]
	v_lshlrev_b64 v[186:187], 12, v[186:187]
	v_lshlrev_b64 v[188:189], 12, v[188:189]
	v_lshlrev_b64 v[190:191], 12, v[190:191]
	v_lshlrev_b64 v[192:193], 12, v[192:193]
	v_lshl_add_u64 v[178:179], v[176:177], 0, v[178:179]
	v_lshl_add_u64 v[180:181], v[176:177], 0, v[180:181]
	v_lshl_add_u64 v[182:183], v[176:177], 0, v[182:183]
	v_lshl_add_u64 v[184:185], v[176:177], 0, v[184:185]
	v_lshl_add_u64 v[186:187], v[176:177], 0, v[186:187]
	v_lshl_add_u64 v[188:189], v[176:177], 0, v[188:189]
	v_lshl_add_u64 v[190:191], v[176:177], 0, v[190:191]
	v_lshl_add_u64 v[192:193], v[176:177], 0, v[192:193]
	global_load_dword v202, v[178:179], off nt
	global_load_dword v203, v[180:181], off nt
	global_load_dword v204, v[182:183], off nt
	global_load_dword v205, v[184:185], off nt
	global_load_dword v206, v[186:187], off nt
	global_load_dword v207, v[188:189], off nt
	global_load_dword v208, v[190:191], off nt
	global_load_dword v209, v[192:193], off nt
	v_or_b32_e32 v178, 32, v174
	v_or_b32_e32 v180, 34, v174
	v_or_b32_e32 v182, 36, v174
	v_or_b32_e32 v184, 38, v174
	v_or_b32_e32 v186, 40, v174
	v_or_b32_e32 v188, 42, v174
	v_or_b32_e32 v190, 44, v174
	v_or_b32_e32 v192, 46, v174
	v_ashrrev_i32_e32 v179, 31, v178
	v_ashrrev_i32_e32 v181, 31, v180
	v_ashrrev_i32_e32 v183, 31, v182
	v_ashrrev_i32_e32 v185, 31, v184
	v_ashrrev_i32_e32 v187, 31, v186
	v_ashrrev_i32_e32 v189, 31, v188
	v_ashrrev_i32_e32 v191, 31, v190
	v_ashrrev_i32_e32 v193, 31, v192
	v_lshlrev_b64 v[178:179], 12, v[178:179]
; #define LAS __attribute__((address_space(3)))
; #define LDS_WAIT() asm volatile("s_waitcnt lgkmcnt(0)" ::: "memory")
; __device__ __forceinline__ unsigned pk2(float lo, float hi) { return pg8::cvt_pk_bf16(lo, hi); }
; template <bool PERMUTE>
; __device__ __forceinline__ void p0_transpose_item(const float* W, int K, int N, bf16* WT, LAS float* scr, int item, int lane) {
;     ...
;     for (int i = 0; i < 32; ++i) wv[i] = __builtin_nontemporal_load(W + (size_t)(k0 + 2 * i + (lane >> 5)) * N + n0 + (lane & 31));
; #pragma unroll
;     for (int i = 0; i < 32; ++i) scr[(2 * i + (lane >> 5)) * 33 + (lane & 31)] = wv[i];
;     LDS_WAIT(); asm volatile("" ::: "memory");
;     const int c = lane & 7;
; #pragma unroll
;     for (int j = 0; j < 4; ++j) { const int n = (lane >> 3) + 8 * j; const LAS float* s = scr + (8 * c) * 33 + n;
;         v4u o; o.x = pk2(s[0 * 33], s[1 * 33]); o.y = pk2(s[2 * 33], s[3 * 33]); o.z = pk2(s[4 * 33], s[5 * 33]); o.w = pk2(s[6 * 33], s[7 * 33]);
;         const int dr = PERMUTE ? win_dst_row(n0 + n) : (n0 + n);
;         if (PERMUTE && n0 < 4096) __builtin_nontemporal_store(o, (v4u*)(WT + (size_t)dr * K + k0 + 8 * c));
;         else *(v4u*)(WT + (size_t)dr * K + k0 + 8 * c) = o; }
;     LDS_WAIT(); asm volatile("" ::: "memory");
	v_lshlrev_b64 v[180:181], 12, v[180:181]
	v_lshlrev_b64 v[182:183], 12, v[182:183]
	v_lshlrev_b64 v[184:185], 12, v[184:185]
	v_lshlrev_b64 v[186:187], 12, v[186:187]
	v_lshlrev_b64 v[188:189], 12, v[188:189]
	v_lshlrev_b64 v[190:191], 12, v[190:191]
	v_lshlrev_b64 v[192:193], 12, v[192:193]
	v_lshl_add_u64 v[178:179], v[176:177], 0, v[178:179]
	v_lshl_add_u64 v[180:181], v[176:177], 0, v[180:181]
	v_lshl_add_u64 v[182:183], v[176:177], 0, v[182:183]
	v_lshl_add_u64 v[184:185], v[176:177], 0, v[184:185]
	v_lshl_add_u64 v[186:187], v[176:177], 0, v[186:187]
	v_lshl_add_u64 v[188:189], v[176:177], 0, v[188:189]
	v_lshl_add_u64 v[190:191], v[176:177], 0, v[190:191]
	v_lshl_add_u64 v[192:193], v[176:177], 0, v[192:193]
	global_load_dword v210, v[178:179], off nt
	global_load_dword v211, v[180:181], off nt
	global_load_dword v212, v[182:183], off nt
	global_load_dword v213, v[184:185], off nt
	global_load_dword v214, v[186:187], off nt
	global_load_dword v215, v[188:189], off nt
	global_load_dword v216, v[190:191], off nt
	s_nop 0
	global_load_dword v192, v[192:193], off nt
	v_or_b32_e32 v178, 48, v174
	v_or_b32_e32 v180, 50, v174
	v_or_b32_e32 v182, 52, v174
	v_or_b32_e32 v184, 54, v174
	v_or_b32_e32 v186, 56, v174
	v_or_b32_e32 v188, 58, v174
	v_or_b32_e32 v190, 60, v174
	v_or_b32_e32 v174, 62, v174
	v_ashrrev_i32_e32 v179, 31, v178
	v_ashrrev_i32_e32 v181, 31, v180
	v_ashrrev_i32_e32 v183, 31, v182
	v_ashrrev_i32_e32 v175, 31, v174
	v_lshlrev_b64 v[178:179], 12, v[178:179]
	v_lshlrev_b64 v[180:181], 12, v[180:181]
	v_lshlrev_b64 v[182:183], 12, v[182:183]
	v_ashrrev_i32_e32 v185, 31, v184
	v_ashrrev_i32_e32 v187, 31, v186
	v_ashrrev_i32_e32 v189, 31, v188
	v_ashrrev_i32_e32 v191, 31, v190
	v_lshlrev_b64 v[174:175], 12, v[174:175]
	v_lshl_add_u64 v[178:179], v[176:177], 0, v[178:179]
	v_lshl_add_u64 v[180:181], v[176:177], 0, v[180:181]
	v_lshl_add_u64 v[182:183], v[176:177], 0, v[182:183]
	v_lshlrev_b64 v[184:185], 12, v[184:185]
	v_lshlrev_b64 v[186:187], 12, v[186:187]
	v_lshlrev_b64 v[188:189], 12, v[188:189]
	v_lshlrev_b64 v[190:191], 12, v[190:191]
	v_lshl_add_u64 v[174:175], v[176:177], 0, v[174:175]
	v_lshl_add_u64 v[184:185], v[176:177], 0, v[184:185]
	v_lshl_add_u64 v[186:187], v[176:177], 0, v[186:187]
	v_lshl_add_u64 v[188:189], v[176:177], 0, v[188:189]
	v_lshl_add_u64 v[190:191], v[176:177], 0, v[190:191]
	global_load_dword v176, v[178:179], off nt
	global_load_dword v177, v[180:181], off nt
	s_nop 0
	global_load_dword v178, v[182:183], off nt
	global_load_dword v179, v[184:185], off nt
	global_load_dword v180, v[186:187], off nt
	global_load_dword v181, v[188:189], off nt
	s_nop 0
	global_load_dword v182, v[190:191], off nt
	s_nop 0
	global_load_dword v174, v[174:175], off nt
	v_mul_u32_u24_e32 v3, 0x84, v136
	v_readlane_b32 s1, v253, 30
	s_ashr_i32 s3, s2, 31
	s_lshl_b64 s[2:3], s[2:3], 1
	v_add3_u32 v0, s1, v0, v3
	v_add_u32_e32 v3, 0x400, v0
	s_waitcnt vmcnt(62)
	ds_write2_b32 v0, v22, v23 offset1:66
	s_waitcnt vmcnt(60)
	ds_write2_b32 v0, v24, v25 offset0:132 offset1:198
	s_waitcnt vmcnt(58)
	ds_write2_b32 v3, v26, v27 offset0:8 offset1:74
	s_waitcnt vmcnt(56)
	ds_write2_b32 v3, v28, v29 offset0:140 offset1:206
	v_add_u32_e32 v3, 0x800, v0
	s_waitcnt vmcnt(54)
	ds_write2_b32 v3, v30, v31 offset0:16 offset1:82
	s_waitcnt vmcnt(52)
	ds_write2_b32 v3, v32, v33 offset0:148 offset1:214
	v_add_u32_e32 v3, 0xc00, v0
	s_waitcnt vmcnt(50)
	ds_write2_b32 v3, v34, v35 offset0:24 offset1:90
	s_waitcnt vmcnt(48)
	ds_write2_b32 v3, v36, v37 offset0:156 offset1:222
	v_add_u32_e32 v3, 0x1000, v0
	s_waitcnt vmcnt(46)
	ds_write2_b32 v3, v38, v39 offset0:32 offset1:98
	s_waitcnt vmcnt(44)
	ds_write2_b32 v3, v40, v41 offset0:164 offset1:230
	v_add_u32_e32 v3, 0x1400, v0
	s_waitcnt vmcnt(42)
	ds_write2_b32 v3, v42, v43 offset0:40 offset1:106
	s_waitcnt vmcnt(40)
	ds_write2_b32 v3, v44, v20 offset0:172 offset1:238
	v_add_u32_e32 v3, 0x1800, v0
	v_add_u32_e32 v0, 0x1c00, v0
	s_waitcnt vmcnt(38)
	ds_write2_b32 v3, v4, v5 offset0:48 offset1:114
	s_waitcnt vmcnt(36)
	ds_write2_b32 v3, v6, v7 offset0:180 offset1:246
	s_waitcnt vmcnt(34)
	ds_write2_b32 v0, v8, v9 offset0:56 offset1:122
	s_waitcnt vmcnt(32)
	ds_write2_b32 v0, v10, v2 offset0:188 offset1:254
	s_waitcnt lgkmcnt(0)
	v_mul_u32_u24_e32 v0, 0x84, v130
	v_lshlrev_b32_e32 v2, 2, v127
	v_add3_u32 v12, s1, v0, v2
	ds_read2_b32 v[2:3], v12 offset1:33
	s_waitcnt lgkmcnt(0)
	v_cvt_pk_bf16_f32 v2, v2, v3
	ds_read2_b32 v[4:5], v12 offset0:66 offset1:99
	s_waitcnt lgkmcnt(0)
	v_cvt_pk_bf16_f32 v3, v4, v5
	ds_read2_b32 v[4:5], v12 offset0:132 offset1:165
	s_waitcnt lgkmcnt(0)
	v_cvt_pk_bf16_f32 v4, v4, v5
	ds_read2_b32 v[6:7], v12 offset0:198 offset1:231
	v_readlane_b32 s4, v253, 48
	v_readlane_b32 s5, v253, 49
	s_add_u32 s2, s4, s2
	s_waitcnt lgkmcnt(0)
	v_cvt_pk_bf16_f32 v5, v6, v7
	v_or_b32_e32 v6, s0, v127
	s_addc_u32 s3, s5, s3
	v_mov_b32_e32 v99, v1
	v_ashrrev_i32_e32 v7, 31, v6
	v_lshl_add_u64 v[8:9], s[2:3], 0, v[98:99]
	v_lshlrev_b64 v[10:11], 12, v[6:7]
	ds_read2_b32 v[0:1], v12 offset0:8 offset1:41
	v_lshl_add_u64 v[10:11], v[8:9], 0, v[10:11]
	global_store_dwordx4 v[10:11], v[2:5], off
	s_waitcnt lgkmcnt(0)
	v_cvt_pk_bf16_f32 v0, v0, v1
	ds_read2_b32 v[2:3], v12 offset0:74 offset1:107
	s_waitcnt lgkmcnt(0)
	v_cvt_pk_bf16_f32 v1, v2, v3
	ds_read2_b32 v[2:3], v12 offset0:140 offset1:173
	s_waitcnt lgkmcnt(0)
	v_cvt_pk_bf16_f32 v2, v2, v3
	ds_read2_b32 v[4:5], v12 offset0:206 offset1:239
	s_waitcnt lgkmcnt(0)
	v_cvt_pk_bf16_f32 v3, v4, v5
	v_or_b32_e32 v4, 8, v6
	v_ashrrev_i32_e32 v5, 31, v4
	v_lshlrev_b64 v[4:5], 12, v[4:5]
	v_lshl_add_u64 v[4:5], v[8:9], 0, v[4:5]
	ds_read2_b32 v[10:11], v12 offset0:16 offset1:49
	global_store_dwordx4 v[4:5], v[0:3], off
	v_readlane_b32 s13, v253, 5
	v_readlane_b32 s14, v253, 6
	s_waitcnt lgkmcnt(0)
; #define LAS __attribute__((address_space(3)))
; #define LDS_WAIT() asm volatile("s_waitcnt lgkmcnt(0)" ::: "memory")
; __device__ __forceinline__ unsigned pk2(float lo, float hi) { return pg8::cvt_pk_bf16(lo, hi); }
; template <bool PERMUTE>
; __device__ __forceinline__ void p0_transpose_item(const float* W, int K, int N, bf16* WT, LAS float* scr, int item, int lane) {
;     const int nblk = N / 32, kb = item / nblk, nb = item % nblk, k0 = 64 * kb, n0 = 32 * nb;
;     float wv[32];
; #pragma unroll
;     for (int i = 0; i < 32; ++i) wv[i] = __builtin_nontemporal_load(W + (size_t)(k0 + 2 * i + (lane >> 5)) * N + n0 + (lane & 31));
; #pragma unroll
;     for (int i = 0; i < 32; ++i) scr[(2 * i + (lane >> 5)) * 33 + (lane & 31)] = wv[i];
;     LDS_WAIT(); asm volatile("" ::: "memory");
;     const int c = lane & 7;
; #pragma unroll
;     for (int j = 0; j < 4; ++j) { const int n = (lane >> 3) + 8 * j; const LAS float* s = scr + (8 * c) * 33 + n;
;         v4u o; o.x = pk2(s[0 * 33], s[1 * 33]); o.y = pk2(s[2 * 33], s[3 * 33]); o.z = pk2(s[4 * 33], s[5 * 33]); o.w = pk2(s[6 * 33], s[7 * 33]);
;         const int dr = PERMUTE ? win_dst_row(n0 + n) : (n0 + n);
;         if (PERMUTE && n0 < 4096) __builtin_nontemporal_store(o, (v4u*)(WT + (size_t)dr * K + k0 + 8 * c));
;         else *(v4u*)(WT + (size_t)dr * K + k0 + 8 * c) = o; }
;     LDS_WAIT(); asm volatile("" ::: "memory");
	v_cvt_pk_bf16_f32 v0, v10, v11
	ds_read2_b32 v[2:3], v12 offset0:82 offset1:115
	s_waitcnt lgkmcnt(0)
	v_cvt_pk_bf16_f32 v1, v2, v3
	ds_read2_b32 v[2:3], v12 offset0:148 offset1:181
	s_waitcnt lgkmcnt(0)
	v_cvt_pk_bf16_f32 v2, v2, v3
	ds_read2_b32 v[4:5], v12 offset0:214 offset1:247
	s_waitcnt lgkmcnt(0)
	v_cvt_pk_bf16_f32 v3, v4, v5
	v_or_b32_e32 v4, 16, v6
	v_ashrrev_i32_e32 v5, 31, v4
	v_lshlrev_b64 v[4:5], 12, v[4:5]
	v_lshl_add_u64 v[4:5], v[8:9], 0, v[4:5]
	ds_read2_b32 v[10:11], v12 offset0:24 offset1:57
	global_store_dwordx4 v[4:5], v[0:3], off
	v_readlane_b32 s15, v253, 7
	v_readlane_b32 s16, v253, 8
	s_waitcnt lgkmcnt(0)
	v_cvt_pk_bf16_f32 v0, v10, v11
	ds_read2_b32 v[2:3], v12 offset0:90 offset1:123
	s_waitcnt lgkmcnt(0)
	v_cvt_pk_bf16_f32 v1, v2, v3
	ds_read2_b32 v[2:3], v12 offset0:156 offset1:189
	s_waitcnt lgkmcnt(0)
	v_cvt_pk_bf16_f32 v2, v2, v3
	ds_read2_b32 v[4:5], v12 offset0:222 offset1:255
	s_waitcnt lgkmcnt(0)
	v_cvt_pk_bf16_f32 v3, v4, v5
	v_or_b32_e32 v4, 24, v6
	v_ashrrev_i32_e32 v5, 31, v4
	v_lshlrev_b64 v[4:5], 12, v[4:5]
	v_lshl_add_u64 v[4:5], v[8:9], 0, v[4:5]
	global_store_dwordx4 v[4:5], v[0:3], off
	s_waitcnt lgkmcnt(0)
	v_readlane_b32 s17, v253, 9
	v_readlane_b32 s18, v253, 10
	v_readlane_b32 s19, v253, 11
	v_readlane_b32 s20, v253, 12
	v_readlane_b32 s21, v253, 13
	v_readlane_b32 s22, v253, 14
	v_readlane_b32 s23, v253, 15
	v_readlane_b32 s24, v253, 16
	v_readlane_b32 s25, v253, 17
	s_mov_b32 s2, s6
	s_mov_b32 s0, s10
	v_mul_u32_u24_e32 v175, 0x84, v136
	v_readlane_b32 s1, v253, 30
	s_ashr_i32 s3, s2, 31
	s_lshl_b64 s[2:3], s[2:3], 1
	v_add3_u32 v172, s1, v172, v175
	v_add_u32_e32 v175, 0x400, v172
	s_waitcnt vmcnt(30)
	ds_write2_b32 v172, v194, v195 offset1:66
	s_waitcnt vmcnt(28)
	ds_write2_b32 v172, v196, v197 offset0:132 offset1:198
	s_waitcnt vmcnt(26)
	ds_write2_b32 v175, v198, v199 offset0:8 offset1:74
	s_waitcnt vmcnt(24)
	ds_write2_b32 v175, v200, v201 offset0:140 offset1:206
	v_add_u32_e32 v175, 0x800, v172
	s_waitcnt vmcnt(22)
	ds_write2_b32 v175, v202, v203 offset0:16 offset1:82
	s_waitcnt vmcnt(20)
	ds_write2_b32 v175, v204, v205 offset0:148 offset1:214
	v_add_u32_e32 v175, 0xc00, v172
	s_waitcnt vmcnt(18)
	ds_write2_b32 v175, v206, v207 offset0:24 offset1:90
	s_waitcnt vmcnt(16)
	ds_write2_b32 v175, v208, v209 offset0:156 offset1:222
	v_add_u32_e32 v175, 0x1000, v172
	s_waitcnt vmcnt(14)
	ds_write2_b32 v175, v210, v211 offset0:32 offset1:98
	s_waitcnt vmcnt(12)
	ds_write2_b32 v175, v212, v213 offset0:164 offset1:230
	v_add_u32_e32 v175, 0x1400, v172
	s_waitcnt vmcnt(10)
	ds_write2_b32 v175, v214, v215 offset0:40 offset1:106
	s_waitcnt vmcnt(8)
	ds_write2_b32 v175, v216, v192 offset0:172 offset1:238
	v_add_u32_e32 v175, 0x1800, v172
	v_add_u32_e32 v172, 0x1c00, v172
	s_waitcnt vmcnt(6)
	ds_write2_b32 v175, v176, v177 offset0:48 offset1:114
	s_waitcnt vmcnt(4)
	ds_write2_b32 v175, v178, v179 offset0:180 offset1:246
	s_waitcnt vmcnt(2)
	ds_write2_b32 v172, v180, v181 offset0:56 offset1:122
	s_waitcnt vmcnt(0)
	ds_write2_b32 v172, v182, v174 offset0:188 offset1:254
	s_waitcnt lgkmcnt(0)
	v_mul_u32_u24_e32 v172, 0x84, v130
	v_lshlrev_b32_e32 v174, 2, v127
	v_add3_u32 v184, s1, v172, v174
	ds_read2_b32 v[174:175], v184 offset1:33
	s_waitcnt lgkmcnt(0)
	v_cvt_pk_bf16_f32 v174, v174, v175
	ds_read2_b32 v[176:177], v184 offset0:66 offset1:99
	s_waitcnt lgkmcnt(0)
	v_cvt_pk_bf16_f32 v175, v176, v177
	ds_read2_b32 v[176:177], v184 offset0:132 offset1:165
	s_waitcnt lgkmcnt(0)
	v_cvt_pk_bf16_f32 v176, v176, v177
	ds_read2_b32 v[178:179], v184 offset0:198 offset1:231
	v_readlane_b32 s4, v253, 48
	v_readlane_b32 s5, v253, 49
	s_add_u32 s2, s4, s2
	s_waitcnt lgkmcnt(0)
	v_cvt_pk_bf16_f32 v177, v178, v179
	v_or_b32_e32 v178, s0, v127
	s_addc_u32 s3, s5, s3
	v_mov_b32_e32 v99, v173
	v_ashrrev_i32_e32 v179, 31, v178
	v_lshl_add_u64 v[180:181], s[2:3], 0, v[98:99]
	v_lshlrev_b64 v[182:183], 12, v[178:179]
	ds_read2_b32 v[172:173], v184 offset0:8 offset1:41
	v_lshl_add_u64 v[182:183], v[180:181], 0, v[182:183]
	global_store_dwordx4 v[182:183], v[174:177], off
	s_waitcnt lgkmcnt(0)
	v_cvt_pk_bf16_f32 v172, v172, v173
	ds_read2_b32 v[174:175], v184 offset0:74 offset1:107
	s_waitcnt lgkmcnt(0)
	v_cvt_pk_bf16_f32 v173, v174, v175
	ds_read2_b32 v[174:175], v184 offset0:140 offset1:173
	s_waitcnt lgkmcnt(0)
	v_cvt_pk_bf16_f32 v174, v174, v175
	ds_read2_b32 v[176:177], v184 offset0:206 offset1:239
	s_waitcnt lgkmcnt(0)
	v_cvt_pk_bf16_f32 v175, v176, v177
	v_or_b32_e32 v176, 8, v178
	v_ashrrev_i32_e32 v177, 31, v176
	v_lshlrev_b64 v[176:177], 12, v[176:177]
	v_lshl_add_u64 v[176:177], v[180:181], 0, v[176:177]
	ds_read2_b32 v[182:183], v184 offset0:16 offset1:49
	global_store_dwordx4 v[176:177], v[172:175], off
	v_readlane_b32 s13, v253, 5
	v_readlane_b32 s14, v253, 6
	s_waitcnt lgkmcnt(0)
	v_cvt_pk_bf16_f32 v172, v182, v183
	ds_read2_b32 v[174:175], v184 offset0:82 offset1:115
	s_waitcnt lgkmcnt(0)
	v_cvt_pk_bf16_f32 v173, v174, v175
	ds_read2_b32 v[174:175], v184 offset0:148 offset1:181
	s_waitcnt lgkmcnt(0)
	v_cvt_pk_bf16_f32 v174, v174, v175
	ds_read2_b32 v[176:177], v184 offset0:214 offset1:247
	s_waitcnt lgkmcnt(0)
	v_cvt_pk_bf16_f32 v175, v176, v177
	v_or_b32_e32 v176, 16, v178
	v_ashrrev_i32_e32 v177, 31, v176
	v_lshlrev_b64 v[176:177], 12, v[176:177]
	v_lshl_add_u64 v[176:177], v[180:181], 0, v[176:177]
	ds_read2_b32 v[182:183], v184 offset0:24 offset1:57
	global_store_dwordx4 v[176:177], v[172:175], off
	v_readlane_b32 s15, v253, 7
	v_readlane_b32 s16, v253, 8
	s_waitcnt lgkmcnt(0)
	v_cvt_pk_bf16_f32 v172, v182, v183
	ds_read2_b32 v[174:175], v184 offset0:90 offset1:123
	s_waitcnt lgkmcnt(0)
	v_cvt_pk_bf16_f32 v173, v174, v175
	ds_read2_b32 v[174:175], v184 offset0:156 offset1:189
	s_waitcnt lgkmcnt(0)
	v_cvt_pk_bf16_f32 v174, v174, v175
	ds_read2_b32 v[176:177], v184 offset0:222 offset1:255
	s_waitcnt lgkmcnt(0)
	v_cvt_pk_bf16_f32 v175, v176, v177
	v_or_b32_e32 v176, 24, v178
	v_ashrrev_i32_e32 v177, 31, v176
	v_lshlrev_b64 v[176:177], 12, v[176:177]
	v_lshl_add_u64 v[176:177], v[180:181], 0, v[176:177]
	global_store_dwordx4 v[176:177], v[172:175], off
	s_waitcnt lgkmcnt(0)
	v_readlane_b32 s17, v253, 9
	v_readlane_b32 s18, v253, 10
	v_readlane_b32 s19, v253, 11
	v_readlane_b32 s20, v253, 12
	v_readlane_b32 s21, v253, 13
	v_readlane_b32 s22, v253, 14
	v_readlane_b32 s23, v253, 15
	v_readlane_b32 s24, v253, 16
	v_readlane_b32 s25, v253, 17
	s_barrier
	s_branch .LBB0_303
